# same as previous plus one wait state between the last weight pack and the second PV MFMA of component 1 (hazard margin)
# baseline (speedup 1.0000x reference)
.Latt_a_main:
	s_waitcnt lgkmcnt(6)
	v_mfma_f32_32x32x16_bf16 v[132:147], v[180:183], v[184:187], v[148:163]
	ds_read_b128 v[180:183], v249
	ds_read_b128 v[184:187], v219 offset:3072
	s_waitcnt lgkmcnt(6)
	v_mfma_f32_32x32x16_bf16 v[148:163], v[188:191], v[192:195], v[148:163]
	ds_read_b128 v[188:191], v251
	ds_read_b128 v[192:195], v219 offset:5120
	s_waitcnt lgkmcnt(6)
	v_mfma_f32_32x32x16_bf16 v[148:163], v[200:203], v[204:207], v[148:163]
	ds_read_b128 v[200:203], v252
	ds_read_b128 v[204:207], v219 offset:6144
	s_waitcnt lgkmcnt(6)
	v_mfma_f32_32x32x16_bf16 v[148:163], v[208:211], v[212:215], v[148:163]
	ds_read_b128 v[208:211], v253
	ds_read_b128 v[212:215], v219 offset:7168
	s_waitcnt lgkmcnt(6)
	v_mfma_f32_32x32x16_bf16 v[148:163], v[180:183], v[184:187], v[148:163]
	ds_read_b64_tr_b16 v[180:181], v228 offset:32768
	ds_read_b64_tr_b16 v[182:183], v228 offset:33280
	ds_read_b64_tr_b16 v[184:185], v228 offset:33792
	ds_read_b64_tr_b16 v[186:187], v228 offset:34304
	s_waitcnt lgkmcnt(8)
	v_mfma_f32_32x32x16_bf16 v[132:147], v[188:191], v[192:195], v[132:147]
	ds_read_b64_tr_b16 v[188:189], v228 offset:36864
	ds_read_b64_tr_b16 v[190:191], v228 offset:37376
	ds_read_b64_tr_b16 v[192:193], v228 offset:37888
	ds_read_b64_tr_b16 v[194:195], v228 offset:38400
	s_waitcnt lgkmcnt(10)
	v_mfma_f32_32x32x16_bf16 v[132:147], v[200:203], v[204:207], v[132:147]
	ds_read_b64_tr_b16 v[200:201], v228 offset:40960
	ds_read_b64_tr_b16 v[202:203], v228 offset:41472
	ds_read_b64_tr_b16 v[204:205], v228 offset:41984
	ds_read_b64_tr_b16 v[206:207], v228 offset:42496
	s_waitcnt lgkmcnt(12)
	v_mfma_f32_32x32x16_bf16 v[132:147], v[208:211], v[212:215], v[132:147]
	ds_read_b64_tr_b16 v[208:209], v228 offset:45056
	ds_read_b64_tr_b16 v[210:211], v228 offset:45568
	v_exp_f32_e32 v148, v148
	v_exp_f32_e32 v149, v149
	v_exp_f32_e32 v150, v150
	v_exp_f32_e32 v151, v151
	v_exp_f32_e32 v152, v152
	v_exp_f32_e32 v153, v153
	v_exp_f32_e32 v154, v154
	v_exp_f32_e32 v155, v155
	v_exp_f32_e32 v156, v156
	v_exp_f32_e32 v157, v157
	v_exp_f32_e32 v158, v158
	v_exp_f32_e32 v159, v159
	v_exp_f32_e32 v160, v160
	v_exp_f32_e32 v161, v161
	v_exp_f32_e32 v162, v162
	v_exp_f32_e32 v163, v163
	v_add_f32_e32 v170, v170, v148
	v_add_f32_e32 v171, v171, v149
	v_cvt_pk_bf16_f32 v230, v148, v149
	v_add_f32_e32 v170, v170, v150
	v_add_f32_e32 v171, v171, v151
	v_cvt_pk_bf16_f32 v231, v150, v151
	v_add_f32_e32 v170, v170, v152
	v_add_f32_e32 v171, v171, v153
	v_cvt_pk_bf16_f32 v232, v152, v153
	v_add_f32_e32 v170, v170, v154
	v_add_f32_e32 v171, v171, v155
	v_cvt_pk_bf16_f32 v233, v154, v155
	v_add_f32_e32 v170, v170, v156
	v_add_f32_e32 v171, v171, v157
	v_cvt_pk_bf16_f32 v234, v156, v157
	v_add_f32_e32 v170, v170, v158
	v_add_f32_e32 v171, v171, v159
	v_cvt_pk_bf16_f32 v235, v158, v159
	v_add_f32_e32 v170, v170, v160
	v_add_f32_e32 v171, v171, v161
	v_cvt_pk_bf16_f32 v236, v160, v161
	v_add_f32_e32 v170, v170, v162
	v_add_f32_e32 v171, v171, v163
	v_cvt_pk_bf16_f32 v237, v162, v163
	s_waitcnt lgkmcnt(12)
	ds_read_b64_tr_b16 v[212:213], v228 offset:46080
	ds_read_b64_tr_b16 v[214:215], v228 offset:46592
	s_setprio 2
	v_mfma_f32_32x32x16_bf16 v[100:115], v[180:183], v[230:233], v[100:115]
	v_exp_f32_e32 v132, v132
	v_exp_f32_e32 v133, v133
	s_waitcnt lgkmcnt(12)
	v_mfma_f32_32x32x16_bf16 v[100:115], v[184:187], v[234:237], v[100:115]
	v_exp_f32_e32 v134, v134
	v_exp_f32_e32 v135, v135
	v_add_f32_e32 v178, v178, v132
	v_add_f32_e32 v179, v179, v133
	v_cvt_pk_bf16_f32 v238, v132, v133
	s_waitcnt lgkmcnt(10)
	v_mfma_f32_32x32x16_bf16 v[68:83], v[188:191], v[230:233], v[68:83]
	v_exp_f32_e32 v136, v136
	v_exp_f32_e32 v137, v137
	v_add_f32_e32 v178, v178, v134
	v_add_f32_e32 v179, v179, v135
	v_cvt_pk_bf16_f32 v239, v134, v135
	s_waitcnt lgkmcnt(8)
	v_mfma_f32_32x32x16_bf16 v[68:83], v[192:195], v[234:237], v[68:83]
	v_exp_f32_e32 v138, v138
	v_exp_f32_e32 v139, v139
	v_add_f32_e32 v178, v178, v136
	v_add_f32_e32 v179, v179, v137
	v_cvt_pk_bf16_f32 v240, v136, v137
	s_waitcnt lgkmcnt(6)
	v_mfma_f32_32x32x16_bf16 v[34:49], v[200:203], v[230:233], v[34:49]
	v_exp_f32_e32 v140, v140
	v_exp_f32_e32 v141, v141
	v_add_f32_e32 v178, v178, v138
	v_add_f32_e32 v179, v179, v139
	v_cvt_pk_bf16_f32 v241, v138, v139
	s_waitcnt lgkmcnt(4)
	v_mfma_f32_32x32x16_bf16 v[34:49], v[204:207], v[234:237], v[34:49]
	v_exp_f32_e32 v142, v142
	v_exp_f32_e32 v143, v143
	v_add_f32_e32 v178, v178, v140
	v_add_f32_e32 v179, v179, v141
	v_cvt_pk_bf16_f32 v242, v140, v141
	s_waitcnt lgkmcnt(2)
	v_mfma_f32_32x32x16_bf16 v[18:33], v[208:211], v[230:233], v[18:33]
	v_exp_f32_e32 v144, v144
	v_exp_f32_e32 v145, v145
	v_add_f32_e32 v178, v178, v142
	v_add_f32_e32 v179, v179, v143
	v_cvt_pk_bf16_f32 v243, v142, v143
	s_waitcnt lgkmcnt(0)
	v_mfma_f32_32x32x16_bf16 v[18:33], v[212:215], v[234:237], v[18:33]
	v_exp_f32_e32 v146, v146
	v_exp_f32_e32 v147, v147
	v_add_f32_e32 v178, v178, v144
	v_add_f32_e32 v179, v179, v145
	v_cvt_pk_bf16_f32 v244, v144, v145
	s_nop 0
	v_add_f32_e32 v178, v178, v146
	v_add_f32_e32 v179, v179, v147
	v_cvt_pk_bf16_f32 v245, v146, v147
	s_nop 0
	v_mfma_f32_32x32x16_bf16 v[116:131], v[180:183], v[238:241], v[116:131]
	v_add3_u32 v148, s20, v216, 32
	v_sub_u32_e32 v148, v148, v166
	v_mfma_f32_32x32x16_bf16 v[116:131], v[184:187], v[242:245], v[116:131]
	ds_read_b128 v[180:183], v250 offset:8192
	ds_read_b128 v[184:187], v219 offset:4096
	v_cvt_f32_i32_e32 v148, v148
	v_fma_f32 v148, v164, v148, -v221
	v_mfma_f32_32x32x16_bf16 v[84:99], v[188:191], v[238:241], v[84:99]
	v_add_f32_e32 v149, v164, v148
	v_add_f32_e32 v150, v176, v148
	v_add_f32_e32 v151, v177, v149
	v_mfma_f32_32x32x16_bf16 v[84:99], v[192:195], v[242:245], v[84:99]
	ds_read_b128 v[188:191], v246 offset:8192
	ds_read_b128 v[192:195], v219
	v_add_f32_e32 v152, v174, v148
	v_add_f32_e32 v153, v175, v149
	v_add_f32_e32 v154, v174, v150
	v_add_f32_e32 v155, v175, v151
	v_mfma_f32_32x32x16_bf16 v[50:65], v[200:203], v[238:241], v[50:65]
	v_add_f32_e32 v156, v174, v152
	v_add_f32_e32 v157, v175, v153
	v_add_f32_e32 v158, v174, v154
	v_add_f32_e32 v159, v175, v155
	v_mfma_f32_32x32x16_bf16 v[50:65], v[204:207], v[242:245], v[50:65]
	ds_read_b128 v[200:203], v247 offset:8192
	ds_read_b128 v[204:207], v219 offset:1024
	v_add_f32_e32 v160, v174, v156
	v_add_f32_e32 v161, v175, v157
	v_add_f32_e32 v162, v174, v158
	v_add_f32_e32 v163, v175, v159
	v_mfma_f32_32x32x16_bf16 v[2:17], v[208:211], v[238:241], v[2:17]
	v_mfma_f32_32x32x16_bf16 v[2:17], v[212:215], v[242:245], v[2:17]
	ds_read_b128 v[208:211], v248 offset:8192
	ds_read_b128 v[212:215], v219 offset:2048
	s_setprio 0
	s_waitcnt lgkmcnt(6)
	v_mfma_f32_32x32x16_bf16 v[132:147], v[180:183], v[184:187], v[148:163]
	ds_read_b128 v[180:183], v249 offset:8192
	ds_read_b128 v[184:187], v219 offset:3072
	s_waitcnt lgkmcnt(6)
	v_mfma_f32_32x32x16_bf16 v[148:163], v[188:191], v[192:195], v[148:163]
	ds_read_b128 v[188:191], v251 offset:8192
	ds_read_b128 v[192:195], v219 offset:5120
	s_waitcnt lgkmcnt(6)
	v_mfma_f32_32x32x16_bf16 v[148:163], v[200:203], v[204:207], v[148:163]
	ds_read_b128 v[200:203], v252 offset:8192
	ds_read_b128 v[204:207], v219 offset:6144
	s_waitcnt lgkmcnt(6)
	v_mfma_f32_32x32x16_bf16 v[148:163], v[208:211], v[212:215], v[148:163]
	ds_read_b128 v[208:211], v253 offset:8192
	ds_read_b128 v[212:215], v219 offset:7168
	s_waitcnt lgkmcnt(6)
	v_mfma_f32_32x32x16_bf16 v[148:163], v[180:183], v[184:187], v[148:163]
	ds_read_b64_tr_b16 v[180:181], v228 offset:34816
	ds_read_b64_tr_b16 v[182:183], v228 offset:35328
	ds_read_b64_tr_b16 v[184:185], v228 offset:35840
	ds_read_b64_tr_b16 v[186:187], v228 offset:36352
	s_waitcnt lgkmcnt(8)
	v_mfma_f32_32x32x16_bf16 v[132:147], v[188:191], v[192:195], v[132:147]
	ds_read_b64_tr_b16 v[188:189], v228 offset:38912
	ds_read_b64_tr_b16 v[190:191], v228 offset:39424
	ds_read_b64_tr_b16 v[192:193], v228 offset:39936
	ds_read_b64_tr_b16 v[194:195], v228 offset:40448
	s_waitcnt lgkmcnt(10)
	v_mfma_f32_32x32x16_bf16 v[132:147], v[200:203], v[204:207], v[132:147]
	ds_read_b64_tr_b16 v[200:201], v228 offset:43008
	ds_read_b64_tr_b16 v[202:203], v228 offset:43520
	ds_read_b64_tr_b16 v[204:205], v228 offset:44032
	ds_read_b64_tr_b16 v[206:207], v228 offset:44544
	s_waitcnt lgkmcnt(12)
	v_mfma_f32_32x32x16_bf16 v[132:147], v[208:211], v[212:215], v[132:147]
	ds_read_b64_tr_b16 v[208:209], v228 offset:47104
	ds_read_b64_tr_b16 v[210:211], v228 offset:47616
	v_exp_f32_e32 v148, v148
	v_exp_f32_e32 v149, v149
	v_exp_f32_e32 v150, v150
	v_exp_f32_e32 v151, v151
	v_exp_f32_e32 v152, v152
	v_exp_f32_e32 v153, v153
	v_exp_f32_e32 v154, v154
	v_exp_f32_e32 v155, v155
	v_exp_f32_e32 v156, v156
	v_exp_f32_e32 v157, v157
	v_exp_f32_e32 v158, v158
	v_exp_f32_e32 v159, v159
	v_exp_f32_e32 v160, v160
	v_exp_f32_e32 v161, v161
	v_exp_f32_e32 v162, v162
	v_exp_f32_e32 v163, v163
	v_add_f32_e32 v170, v170, v148
	v_add_f32_e32 v171, v171, v149
	v_cvt_pk_bf16_f32 v230, v148, v149
	v_add_f32_e32 v170, v170, v150
	v_add_f32_e32 v171, v171, v151
	v_cvt_pk_bf16_f32 v231, v150, v151
	v_add_f32_e32 v170, v170, v152
	v_add_f32_e32 v171, v171, v153
	v_cvt_pk_bf16_f32 v232, v152, v153
	v_add_f32_e32 v170, v170, v154
	v_add_f32_e32 v171, v171, v155
	v_cvt_pk_bf16_f32 v233, v154, v155
	v_add_f32_e32 v170, v170, v156
	v_add_f32_e32 v171, v171, v157
	v_cvt_pk_bf16_f32 v234, v156, v157
	v_add_f32_e32 v170, v170, v158
	v_add_f32_e32 v171, v171, v159
	v_cvt_pk_bf16_f32 v235, v158, v159
	v_add_f32_e32 v170, v170, v160
	v_add_f32_e32 v171, v171, v161
	v_cvt_pk_bf16_f32 v236, v160, v161
	v_add_f32_e32 v170, v170, v162
	v_add_f32_e32 v171, v171, v163
	v_cvt_pk_bf16_f32 v237, v162, v163
	s_waitcnt lgkmcnt(12)
	ds_read_b64_tr_b16 v[212:213], v228 offset:48128
	ds_read_b64_tr_b16 v[214:215], v228 offset:48640
	s_setprio 2
	v_mfma_f32_32x32x16_bf16 v[100:115], v[180:183], v[230:233], v[100:115]
	v_exp_f32_e32 v132, v132
	v_exp_f32_e32 v133, v133
	s_waitcnt lgkmcnt(12)
	v_mfma_f32_32x32x16_bf16 v[100:115], v[184:187], v[234:237], v[100:115]
	v_exp_f32_e32 v134, v134
	v_exp_f32_e32 v135, v135
	v_add_f32_e32 v178, v178, v132
	v_add_f32_e32 v179, v179, v133
	v_cvt_pk_bf16_f32 v238, v132, v133
	s_waitcnt lgkmcnt(10)
	v_mfma_f32_32x32x16_bf16 v[68:83], v[188:191], v[230:233], v[68:83]
	v_exp_f32_e32 v136, v136
	v_exp_f32_e32 v137, v137
	v_add_f32_e32 v178, v178, v134
	v_add_f32_e32 v179, v179, v135
	v_cvt_pk_bf16_f32 v239, v134, v135
	s_waitcnt lgkmcnt(8)
	v_mfma_f32_32x32x16_bf16 v[68:83], v[192:195], v[234:237], v[68:83]
	v_exp_f32_e32 v138, v138
	v_exp_f32_e32 v139, v139
	v_add_f32_e32 v178, v178, v136
	v_add_f32_e32 v179, v179, v137
	v_cvt_pk_bf16_f32 v240, v136, v137
	s_waitcnt lgkmcnt(6)
	v_mfma_f32_32x32x16_bf16 v[34:49], v[200:203], v[230:233], v[34:49]
	v_exp_f32_e32 v140, v140
	v_exp_f32_e32 v141, v141
	v_add_f32_e32 v178, v178, v138
	v_add_f32_e32 v179, v179, v139
	v_cvt_pk_bf16_f32 v241, v138, v139
	s_waitcnt lgkmcnt(4)
	v_mfma_f32_32x32x16_bf16 v[34:49], v[204:207], v[234:237], v[34:49]
	v_exp_f32_e32 v142, v142
	v_exp_f32_e32 v143, v143
	v_add_f32_e32 v178, v178, v140
	v_add_f32_e32 v179, v179, v141
	v_cvt_pk_bf16_f32 v242, v140, v141
	s_waitcnt lgkmcnt(2)
	v_mfma_f32_32x32x16_bf16 v[18:33], v[208:211], v[230:233], v[18:33]
	v_exp_f32_e32 v144, v144
	v_exp_f32_e32 v145, v145
	v_add_f32_e32 v178, v178, v142
	v_add_f32_e32 v179, v179, v143
	v_cvt_pk_bf16_f32 v243, v142, v143
	s_waitcnt lgkmcnt(0)
	v_mfma_f32_32x32x16_bf16 v[18:33], v[212:215], v[234:237], v[18:33]
	v_exp_f32_e32 v146, v146
	v_exp_f32_e32 v147, v147
	v_add_f32_e32 v178, v178, v144
	v_add_f32_e32 v179, v179, v145
	v_cvt_pk_bf16_f32 v244, v144, v145
	s_nop 0
	v_add_f32_e32 v178, v178, v146
	v_add_f32_e32 v179, v179, v147
	v_cvt_pk_bf16_f32 v245, v146, v147
	s_nop 0
	s_cmp_ge_i32 s13, s77
	s_cbranch_scc1 .Latt_a_flush
	s_cmp_eq_u32 s13, s78
	s_cbranch_scc1 .Latt_a_flush
	s_mov_b32 s101, 1
	s_branch .LBB0_981

.Latt_fast_b:
	s_cmp_eq_u32 s101, 0
	s_cbranch_scc1 .Latt_b_cold
	v_xor_b32_e32 v249, 0x60, v246
	v_xor_b32_e32 v251, 0xa0, v246
	v_xor_b32_e32 v252, 0xc0, v246
	v_xor_b32_e32 v253, 0xe0, v246
	v_add_u32_e32 v228, s15, v222
	s_mov_b32 s101, 0
	s_setprio 2
	v_mfma_f32_32x32x16_bf16 v[100:115], v[180:183], v[230:233], v[100:115]
	v_exp_f32_e32 v132, v132
	v_exp_f32_e32 v133, v133
	s_waitcnt lgkmcnt(12)
	v_mfma_f32_32x32x16_bf16 v[100:115], v[184:187], v[234:237], v[100:115]
	v_exp_f32_e32 v134, v134
	v_exp_f32_e32 v135, v135
	v_add_f32_e32 v178, v178, v132
	v_add_f32_e32 v179, v179, v133
	v_cvt_pk_bf16_f32 v238, v132, v133
	s_waitcnt lgkmcnt(10)
	v_mfma_f32_32x32x16_bf16 v[68:83], v[188:191], v[230:233], v[68:83]
	v_exp_f32_e32 v136, v136
	v_exp_f32_e32 v137, v137
	v_add_f32_e32 v178, v178, v134
	v_add_f32_e32 v179, v179, v135
	v_cvt_pk_bf16_f32 v239, v134, v135
	s_waitcnt lgkmcnt(8)
	v_mfma_f32_32x32x16_bf16 v[68:83], v[192:195], v[234:237], v[68:83]
	v_exp_f32_e32 v138, v138
	v_exp_f32_e32 v139, v139
	v_add_f32_e32 v178, v178, v136
	v_add_f32_e32 v179, v179, v137
	v_cvt_pk_bf16_f32 v240, v136, v137
	s_waitcnt lgkmcnt(6)
	v_mfma_f32_32x32x16_bf16 v[34:49], v[200:203], v[230:233], v[34:49]
	v_exp_f32_e32 v140, v140
	v_exp_f32_e32 v141, v141
	v_add_f32_e32 v178, v178, v138
	v_add_f32_e32 v179, v179, v139
	v_cvt_pk_bf16_f32 v241, v138, v139
	s_waitcnt lgkmcnt(4)
	v_mfma_f32_32x32x16_bf16 v[34:49], v[204:207], v[234:237], v[34:49]
	v_exp_f32_e32 v142, v142
	v_exp_f32_e32 v143, v143
	v_add_f32_e32 v178, v178, v140
	v_add_f32_e32 v179, v179, v141
	v_cvt_pk_bf16_f32 v242, v140, v141
	s_waitcnt lgkmcnt(2)
	v_mfma_f32_32x32x16_bf16 v[18:33], v[208:211], v[230:233], v[18:33]
	v_exp_f32_e32 v144, v144
	v_exp_f32_e32 v145, v145
	v_add_f32_e32 v178, v178, v142
	v_add_f32_e32 v179, v179, v143
	v_cvt_pk_bf16_f32 v243, v142, v143
	s_waitcnt lgkmcnt(0)
	v_mfma_f32_32x32x16_bf16 v[18:33], v[212:215], v[234:237], v[18:33]
	v_exp_f32_e32 v146, v146
	v_exp_f32_e32 v147, v147
	v_add_f32_e32 v178, v178, v144
	v_add_f32_e32 v179, v179, v145
	v_cvt_pk_bf16_f32 v244, v144, v145
	s_nop 0
	v_add_f32_e32 v178, v178, v146
	v_add_f32_e32 v179, v179, v147
	v_cvt_pk_bf16_f32 v245, v146, v147
	s_nop 0
	v_mfma_f32_32x32x16_bf16 v[116:131], v[180:183], v[238:241], v[116:131]
	v_lshl_add_u64 v[132:133], v[172:173], 0, s[16:17]
	s_mov_b32 m0, s39
	s_nop 0
	global_load_lds_dwordx4 v[132:133], off
	v_add_u32_e32 v148, s20, v216
	v_sub_u32_e32 v148, v148, v166
	v_mfma_f32_32x32x16_bf16 v[116:131], v[184:187], v[242:245], v[116:131]
	ds_read_b128 v[180:183], v250
	ds_read_b128 v[184:187], v219 offset:4096
	v_cvt_f32_i32_e32 v148, v148
	v_fma_f32 v148, v164, v148, -v221
	v_mfma_f32_32x32x16_bf16 v[84:99], v[188:191], v[238:241], v[84:99]
	v_lshl_add_u64 v[132:133], v[132:133], 0, v[66:67]
	s_mov_b32 m0, s40
	s_nop 0
	global_load_lds_dwordx4 v[132:133], off
	v_add_f32_e32 v149, v164, v148
	v_add_f32_e32 v150, v176, v148
	v_add_f32_e32 v151, v177, v149
	v_mfma_f32_32x32x16_bf16 v[84:99], v[192:195], v[242:245], v[84:99]
	ds_read_b128 v[188:191], v246
	ds_read_b128 v[192:195], v219
	v_add_f32_e32 v152, v174, v148
	v_add_f32_e32 v153, v175, v149
	v_add_f32_e32 v154, v174, v150
	v_add_f32_e32 v155, v175, v151
	v_mfma_f32_32x32x16_bf16 v[50:65], v[200:203], v[238:241], v[50:65]
	v_lshl_add_u64 v[134:135], v[168:169], 0, s[16:17]
	s_mov_b32 m0, s41
	s_nop 0
	global_load_lds_dwordx4 v[134:135], off
	v_add_f32_e32 v156, v174, v152
	v_add_f32_e32 v157, v175, v153
	v_add_f32_e32 v158, v174, v154
	v_add_f32_e32 v159, v175, v155
	v_mfma_f32_32x32x16_bf16 v[50:65], v[204:207], v[242:245], v[50:65]
	ds_read_b128 v[200:203], v247
	ds_read_b128 v[204:207], v219 offset:1024
	v_add_f32_e32 v160, v174, v156
	v_add_f32_e32 v161, v175, v157
	v_add_f32_e32 v162, v174, v158
	v_add_f32_e32 v163, v175, v159
	v_mfma_f32_32x32x16_bf16 v[2:17], v[208:211], v[238:241], v[2:17]
	v_lshl_add_u64 v[134:135], v[134:135], 0, s[44:45]
	s_mov_b32 m0, s42
	s_nop 0
	global_load_lds_dwordx4 v[134:135], off
	s_mov_b32 m0, s43
	v_mfma_f32_32x32x16_bf16 v[2:17], v[212:215], v[242:245], v[2:17]
	ds_read_b128 v[208:211], v248
	ds_read_b128 v[212:215], v219 offset:2048
	s_setprio 0
	s_branch .Latt_b_main

.Latt_b_main:
	s_waitcnt lgkmcnt(6)
	v_mfma_f32_32x32x16_bf16 v[132:147], v[180:183], v[184:187], v[148:163]
	ds_read_b128 v[180:183], v249
	ds_read_b128 v[184:187], v219 offset:3072
	s_waitcnt lgkmcnt(6)
	v_mfma_f32_32x32x16_bf16 v[148:163], v[188:191], v[192:195], v[148:163]
	ds_read_b128 v[188:191], v251
	ds_read_b128 v[192:195], v219 offset:5120
	s_waitcnt lgkmcnt(6)
	v_mfma_f32_32x32x16_bf16 v[148:163], v[200:203], v[204:207], v[148:163]
	ds_read_b128 v[200:203], v252
	ds_read_b128 v[204:207], v219 offset:6144
	s_waitcnt lgkmcnt(6)
	v_mfma_f32_32x32x16_bf16 v[148:163], v[208:211], v[212:215], v[148:163]
	ds_read_b128 v[208:211], v253
	ds_read_b128 v[212:215], v219 offset:7168
	s_waitcnt lgkmcnt(6)
	v_mfma_f32_32x32x16_bf16 v[148:163], v[180:183], v[184:187], v[148:163]
	ds_read_b64_tr_b16 v[180:181], v228 offset:32768
	ds_read_b64_tr_b16 v[182:183], v228 offset:33280
	ds_read_b64_tr_b16 v[184:185], v228 offset:33792
	ds_read_b64_tr_b16 v[186:187], v228 offset:34304
	s_waitcnt lgkmcnt(8)
	v_mfma_f32_32x32x16_bf16 v[132:147], v[188:191], v[192:195], v[132:147]
	ds_read_b64_tr_b16 v[188:189], v228 offset:36864
	ds_read_b64_tr_b16 v[190:191], v228 offset:37376
	ds_read_b64_tr_b16 v[192:193], v228 offset:37888
	ds_read_b64_tr_b16 v[194:195], v228 offset:38400
	s_waitcnt lgkmcnt(10)
	v_mfma_f32_32x32x16_bf16 v[132:147], v[200:203], v[204:207], v[132:147]
	ds_read_b64_tr_b16 v[200:201], v228 offset:40960
	ds_read_b64_tr_b16 v[202:203], v228 offset:41472
	ds_read_b64_tr_b16 v[204:205], v228 offset:41984
	ds_read_b64_tr_b16 v[206:207], v228 offset:42496
	s_waitcnt lgkmcnt(12)
	v_mfma_f32_32x32x16_bf16 v[132:147], v[208:211], v[212:215], v[132:147]
	ds_read_b64_tr_b16 v[208:209], v228 offset:45056
	ds_read_b64_tr_b16 v[210:211], v228 offset:45568
	v_exp_f32_e32 v148, v148
	v_exp_f32_e32 v149, v149
	v_exp_f32_e32 v150, v150
	v_exp_f32_e32 v151, v151
	v_exp_f32_e32 v152, v152
	v_exp_f32_e32 v153, v153
	v_exp_f32_e32 v154, v154
	v_exp_f32_e32 v155, v155
	v_exp_f32_e32 v156, v156
	v_exp_f32_e32 v157, v157
	v_exp_f32_e32 v158, v158
	v_exp_f32_e32 v159, v159
	v_exp_f32_e32 v160, v160
	v_exp_f32_e32 v161, v161
	v_exp_f32_e32 v162, v162
	v_exp_f32_e32 v163, v163
	v_add_f32_e32 v170, v170, v148
	v_add_f32_e32 v171, v171, v149
	v_cvt_pk_bf16_f32 v230, v148, v149
	v_add_f32_e32 v170, v170, v150
	v_add_f32_e32 v171, v171, v151
	v_cvt_pk_bf16_f32 v231, v150, v151
	v_add_f32_e32 v170, v170, v152
	v_add_f32_e32 v171, v171, v153
	v_cvt_pk_bf16_f32 v232, v152, v153
	v_add_f32_e32 v170, v170, v154
	v_add_f32_e32 v171, v171, v155
	v_cvt_pk_bf16_f32 v233, v154, v155
	v_add_f32_e32 v170, v170, v156
	v_add_f32_e32 v171, v171, v157
	v_cvt_pk_bf16_f32 v234, v156, v157
	v_add_f32_e32 v170, v170, v158
	v_add_f32_e32 v171, v171, v159
	v_cvt_pk_bf16_f32 v235, v158, v159
	v_add_f32_e32 v170, v170, v160
	v_add_f32_e32 v171, v171, v161
	v_cvt_pk_bf16_f32 v236, v160, v161
	v_add_f32_e32 v170, v170, v162
	v_add_f32_e32 v171, v171, v163
	v_cvt_pk_bf16_f32 v237, v162, v163
	s_waitcnt lgkmcnt(12)
	ds_read_b64_tr_b16 v[212:213], v228 offset:46080
	ds_read_b64_tr_b16 v[214:215], v228 offset:46592
	s_setprio 2
	v_mfma_f32_32x32x16_bf16 v[100:115], v[180:183], v[230:233], v[100:115]
	v_exp_f32_e32 v132, v132
	v_exp_f32_e32 v133, v133
	s_waitcnt lgkmcnt(12)
	v_mfma_f32_32x32x16_bf16 v[100:115], v[184:187], v[234:237], v[100:115]
	v_exp_f32_e32 v134, v134
	v_exp_f32_e32 v135, v135
	v_add_f32_e32 v178, v178, v132
	v_add_f32_e32 v179, v179, v133
	v_cvt_pk_bf16_f32 v238, v132, v133
	s_waitcnt lgkmcnt(10)
	v_mfma_f32_32x32x16_bf16 v[68:83], v[188:191], v[230:233], v[68:83]
	v_exp_f32_e32 v136, v136
	v_exp_f32_e32 v137, v137
	v_add_f32_e32 v178, v178, v134
	v_add_f32_e32 v179, v179, v135
	v_cvt_pk_bf16_f32 v239, v134, v135
	s_waitcnt lgkmcnt(8)
	v_mfma_f32_32x32x16_bf16 v[68:83], v[192:195], v[234:237], v[68:83]
	v_exp_f32_e32 v138, v138
	v_exp_f32_e32 v139, v139
	v_add_f32_e32 v178, v178, v136
	v_add_f32_e32 v179, v179, v137
	v_cvt_pk_bf16_f32 v240, v136, v137
	s_waitcnt lgkmcnt(6)
	v_mfma_f32_32x32x16_bf16 v[34:49], v[200:203], v[230:233], v[34:49]
	v_exp_f32_e32 v140, v140
	v_exp_f32_e32 v141, v141
	v_add_f32_e32 v178, v178, v138
	v_add_f32_e32 v179, v179, v139
	v_cvt_pk_bf16_f32 v241, v138, v139
	s_waitcnt lgkmcnt(4)
	v_mfma_f32_32x32x16_bf16 v[34:49], v[204:207], v[234:237], v[34:49]
	v_exp_f32_e32 v142, v142
	v_exp_f32_e32 v143, v143
	v_add_f32_e32 v178, v178, v140
	v_add_f32_e32 v179, v179, v141
	v_cvt_pk_bf16_f32 v242, v140, v141
	s_waitcnt lgkmcnt(2)
	v_mfma_f32_32x32x16_bf16 v[18:33], v[208:211], v[230:233], v[18:33]
	v_exp_f32_e32 v144, v144
	v_exp_f32_e32 v145, v145
	v_add_f32_e32 v178, v178, v142
	v_add_f32_e32 v179, v179, v143
	v_cvt_pk_bf16_f32 v243, v142, v143
	s_waitcnt lgkmcnt(0)
	v_mfma_f32_32x32x16_bf16 v[18:33], v[212:215], v[234:237], v[18:33]
	v_exp_f32_e32 v146, v146
	v_exp_f32_e32 v147, v147
	v_add_f32_e32 v178, v178, v144
	v_add_f32_e32 v179, v179, v145
	v_cvt_pk_bf16_f32 v244, v144, v145
	s_nop 0
	v_add_f32_e32 v178, v178, v146
	v_add_f32_e32 v179, v179, v147
	v_cvt_pk_bf16_f32 v245, v146, v147
	s_nop 0
	v_mfma_f32_32x32x16_bf16 v[116:131], v[180:183], v[238:241], v[116:131]
	v_add3_u32 v148, s20, v216, 32
	v_sub_u32_e32 v148, v148, v166
	v_mfma_f32_32x32x16_bf16 v[116:131], v[184:187], v[242:245], v[116:131]
	ds_read_b128 v[180:183], v250 offset:8192
	ds_read_b128 v[184:187], v219 offset:4096
	v_cvt_f32_i32_e32 v148, v148
	v_fma_f32 v148, v164, v148, -v221
	v_mfma_f32_32x32x16_bf16 v[84:99], v[188:191], v[238:241], v[84:99]
	v_add_f32_e32 v149, v164, v148
	v_add_f32_e32 v150, v176, v148
	v_add_f32_e32 v151, v177, v149
	v_mfma_f32_32x32x16_bf16 v[84:99], v[192:195], v[242:245], v[84:99]
	ds_read_b128 v[188:191], v246 offset:8192
	ds_read_b128 v[192:195], v219
	v_add_f32_e32 v152, v174, v148
	v_add_f32_e32 v153, v175, v149
	v_add_f32_e32 v154, v174, v150
	v_add_f32_e32 v155, v175, v151
	v_mfma_f32_32x32x16_bf16 v[50:65], v[200:203], v[238:241], v[50:65]
	v_add_f32_e32 v156, v174, v152
	v_add_f32_e32 v157, v175, v153
	v_add_f32_e32 v158, v174, v154
	v_add_f32_e32 v159, v175, v155
	v_mfma_f32_32x32x16_bf16 v[50:65], v[204:207], v[242:245], v[50:65]
	ds_read_b128 v[200:203], v247 offset:8192
	ds_read_b128 v[204:207], v219 offset:1024
	v_add_f32_e32 v160, v174, v156
	v_add_f32_e32 v161, v175, v157
	v_add_f32_e32 v162, v174, v158
	v_add_f32_e32 v163, v175, v159
	v_mfma_f32_32x32x16_bf16 v[2:17], v[208:211], v[238:241], v[2:17]
	v_mfma_f32_32x32x16_bf16 v[2:17], v[212:215], v[242:245], v[2:17]
	ds_read_b128 v[208:211], v248 offset:8192
	ds_read_b128 v[212:215], v219 offset:2048
	s_setprio 0
	s_waitcnt lgkmcnt(6)
	v_mfma_f32_32x32x16_bf16 v[132:147], v[180:183], v[184:187], v[148:163]
	ds_read_b128 v[180:183], v249 offset:8192
	ds_read_b128 v[184:187], v219 offset:3072
	s_waitcnt lgkmcnt(6)
	v_mfma_f32_32x32x16_bf16 v[148:163], v[188:191], v[192:195], v[148:163]
	ds_read_b128 v[188:191], v251 offset:8192
	ds_read_b128 v[192:195], v219 offset:5120
	s_waitcnt lgkmcnt(6)
	v_mfma_f32_32x32x16_bf16 v[148:163], v[200:203], v[204:207], v[148:163]
	ds_read_b128 v[200:203], v252 offset:8192
	ds_read_b128 v[204:207], v219 offset:6144
	s_waitcnt lgkmcnt(6)
	v_mfma_f32_32x32x16_bf16 v[148:163], v[208:211], v[212:215], v[148:163]
	ds_read_b128 v[208:211], v253 offset:8192
	ds_read_b128 v[212:215], v219 offset:7168
	s_waitcnt lgkmcnt(6)
	v_mfma_f32_32x32x16_bf16 v[148:163], v[180:183], v[184:187], v[148:163]
	ds_read_b64_tr_b16 v[180:181], v228 offset:34816
	ds_read_b64_tr_b16 v[182:183], v228 offset:35328
	ds_read_b64_tr_b16 v[184:185], v228 offset:35840
	ds_read_b64_tr_b16 v[186:187], v228 offset:36352
	s_waitcnt lgkmcnt(8)
	v_mfma_f32_32x32x16_bf16 v[132:147], v[188:191], v[192:195], v[132:147]
	ds_read_b64_tr_b16 v[188:189], v228 offset:38912
	ds_read_b64_tr_b16 v[190:191], v228 offset:39424
	ds_read_b64_tr_b16 v[192:193], v228 offset:39936
	ds_read_b64_tr_b16 v[194:195], v228 offset:40448
	s_waitcnt lgkmcnt(10)
	v_mfma_f32_32x32x16_bf16 v[132:147], v[200:203], v[204:207], v[132:147]
	ds_read_b64_tr_b16 v[200:201], v228 offset:43008
	ds_read_b64_tr_b16 v[202:203], v228 offset:43520
	ds_read_b64_tr_b16 v[204:205], v228 offset:44032
	ds_read_b64_tr_b16 v[206:207], v228 offset:44544
	s_waitcnt lgkmcnt(12)
	v_mfma_f32_32x32x16_bf16 v[132:147], v[208:211], v[212:215], v[132:147]
	ds_read_b64_tr_b16 v[208:209], v228 offset:47104
	ds_read_b64_tr_b16 v[210:211], v228 offset:47616
	v_exp_f32_e32 v148, v148
	v_exp_f32_e32 v149, v149
	v_exp_f32_e32 v150, v150
	v_exp_f32_e32 v151, v151
	v_exp_f32_e32 v152, v152
	v_exp_f32_e32 v153, v153
	v_exp_f32_e32 v154, v154
	v_exp_f32_e32 v155, v155
	v_exp_f32_e32 v156, v156
	v_exp_f32_e32 v157, v157
	v_exp_f32_e32 v158, v158
	v_exp_f32_e32 v159, v159
	v_exp_f32_e32 v160, v160
	v_exp_f32_e32 v161, v161
	v_exp_f32_e32 v162, v162
	v_exp_f32_e32 v163, v163
	v_add_f32_e32 v170, v170, v148
	v_add_f32_e32 v171, v171, v149
	v_cvt_pk_bf16_f32 v230, v148, v149
	v_add_f32_e32 v170, v170, v150
	v_add_f32_e32 v171, v171, v151
	v_cvt_pk_bf16_f32 v231, v150, v151
	v_add_f32_e32 v170, v170, v152
	v_add_f32_e32 v171, v171, v153
	v_cvt_pk_bf16_f32 v232, v152, v153
	v_add_f32_e32 v170, v170, v154
	v_add_f32_e32 v171, v171, v155
	v_cvt_pk_bf16_f32 v233, v154, v155
	v_add_f32_e32 v170, v170, v156
	v_add_f32_e32 v171, v171, v157
	v_cvt_pk_bf16_f32 v234, v156, v157
	v_add_f32_e32 v170, v170, v158
	v_add_f32_e32 v171, v171, v159
	v_cvt_pk_bf16_f32 v235, v158, v159
	v_add_f32_e32 v170, v170, v160
	v_add_f32_e32 v171, v171, v161
	v_cvt_pk_bf16_f32 v236, v160, v161
	v_add_f32_e32 v170, v170, v162
	v_add_f32_e32 v171, v171, v163
	v_cvt_pk_bf16_f32 v237, v162, v163
	s_waitcnt lgkmcnt(12)
	ds_read_b64_tr_b16 v[212:213], v228 offset:48128
	ds_read_b64_tr_b16 v[214:215], v228 offset:48640
	s_cmp_ge_i32 s13, s77
	s_cbranch_scc1 .Latt_b_flush
	s_cmp_eq_u32 s13, s78
	s_cbranch_scc1 .Latt_b_flush
	s_mov_b32 s101, 1
	s_branch .LBB0_981
.Latt_b_flush:
	s_setprio 2
	v_mfma_f32_32x32x16_bf16 v[100:115], v[180:183], v[230:233], v[100:115]
	v_exp_f32_e32 v132, v132
	v_exp_f32_e32 v133, v133
	s_waitcnt lgkmcnt(12)
	v_mfma_f32_32x32x16_bf16 v[100:115], v[184:187], v[234:237], v[100:115]
	v_exp_f32_e32 v134, v134
	v_exp_f32_e32 v135, v135
	v_add_f32_e32 v178, v178, v132
	v_add_f32_e32 v179, v179, v133
	v_cvt_pk_bf16_f32 v238, v132, v133
	s_waitcnt lgkmcnt(10)
	v_mfma_f32_32x32x16_bf16 v[68:83], v[188:191], v[230:233], v[68:83]
	v_exp_f32_e32 v136, v136
	v_exp_f32_e32 v137, v137
	v_add_f32_e32 v178, v178, v134
	v_add_f32_e32 v179, v179, v135
	v_cvt_pk_bf16_f32 v239, v134, v135
	s_waitcnt lgkmcnt(8)
	v_mfma_f32_32x32x16_bf16 v[68:83], v[192:195], v[234:237], v[68:83]
	v_exp_f32_e32 v138, v138
	v_exp_f32_e32 v139, v139
	v_add_f32_e32 v178, v178, v136
	v_add_f32_e32 v179, v179, v137
	v_cvt_pk_bf16_f32 v240, v136, v137
	s_waitcnt lgkmcnt(6)
	v_mfma_f32_32x32x16_bf16 v[34:49], v[200:203], v[230:233], v[34:49]
	v_exp_f32_e32 v140, v140
	v_exp_f32_e32 v141, v141
	v_add_f32_e32 v178, v178, v138
	v_add_f32_e32 v179, v179, v139
	v_cvt_pk_bf16_f32 v241, v138, v139
	s_waitcnt lgkmcnt(4)
	v_mfma_f32_32x32x16_bf16 v[34:49], v[204:207], v[234:237], v[34:49]
	v_exp_f32_e32 v142, v142
	v_exp_f32_e32 v143, v143
	v_add_f32_e32 v178, v178, v140
	v_add_f32_e32 v179, v179, v141
	v_cvt_pk_bf16_f32 v242, v140, v141
	s_waitcnt lgkmcnt(2)
	v_mfma_f32_32x32x16_bf16 v[18:33], v[208:211], v[230:233], v[18:33]
	v_exp_f32_e32 v144, v144
	v_exp_f32_e32 v145, v145
	v_add_f32_e32 v178, v178, v142
	v_add_f32_e32 v179, v179, v143
	v_cvt_pk_bf16_f32 v243, v142, v143
	s_waitcnt lgkmcnt(0)
	v_mfma_f32_32x32x16_bf16 v[18:33], v[212:215], v[234:237], v[18:33]
	v_exp_f32_e32 v146, v146
	v_exp_f32_e32 v147, v147
	v_add_f32_e32 v178, v178, v144
	v_add_f32_e32 v179, v179, v145
	v_cvt_pk_bf16_f32 v244, v144, v145
	s_nop 0
	v_add_f32_e32 v178, v178, v146
	v_add_f32_e32 v179, v179, v147
	v_cvt_pk_bf16_f32 v245, v146, v147
	s_nop 0
	v_mfma_f32_32x32x16_bf16 v[116:131], v[180:183], v[238:241], v[116:131]
	v_mfma_f32_32x32x16_bf16 v[116:131], v[184:187], v[242:245], v[116:131]
	v_mfma_f32_32x32x16_bf16 v[84:99], v[188:191], v[238:241], v[84:99]
	v_mfma_f32_32x32x16_bf16 v[84:99], v[192:195], v[242:245], v[84:99]
	v_mfma_f32_32x32x16_bf16 v[50:65], v[200:203], v[238:241], v[50:65]
	v_mfma_f32_32x32x16_bf16 v[50:65], v[204:207], v[242:245], v[50:65]
	v_mfma_f32_32x32x16_bf16 v[2:17], v[208:211], v[238:241], v[2:17]
	v_mfma_f32_32x32x16_bf16 v[2:17], v[212:215], v[242:245], v[2:17]
	s_setprio 0
	s_branch .LBB0_981
.Latt_first:
	s_and_b32 s15, s9, 0x4000
	s_max_i32 s20, s73, 0
	v_or_b32_e32 v246, s15, v220
	v_xor_b32_e32 v250, 0x80, v246
	v_xor_b32_e32 v247, 32, v246
	v_xor_b32_e32 v248, 64, v246
	s_sub_i32 s38, s73, 64
	s_max_i32 s74, s38, 0
	s_lshl_b64 s[16:17], s[74:75], 12
	s_add_i32 s38, s9, 0x4000
	s_and_b32 s38, s38, 0x4000
	s_add_i32 s39, s38, s10
	s_add_i32 s40, s39, 0x400
	s_add_i32 s41, s38, s11
	s_add_i32 s42, s41, 0x400
	s_mov_b64 s[44:45], 0x10000
	s_mov_b32 s43, m0
	ds_read_b128 v[180:183], v250
	ds_read_b128 v[184:187], v219 offset:4096
	ds_read_b128 v[188:191], v246
	ds_read_b128 v[192:195], v219
	ds_read_b128 v[200:203], v247
	ds_read_b128 v[204:207], v219 offset:1024
	ds_read_b128 v[208:211], v248
	ds_read_b128 v[212:215], v219 offset:2048
	v_lshl_add_u64 v[132:133], v[172:173], 0, s[16:17]
	s_mov_b32 m0, s39
	s_nop 0
	global_load_lds_dwordx4 v[132:133], off
	v_lshl_add_u64 v[132:133], v[132:133], 0, v[66:67]
	s_mov_b32 m0, s40
	s_nop 0
	global_load_lds_dwordx4 v[132:133], off
	v_lshl_add_u64 v[134:135], v[168:169], 0, s[16:17]
	s_mov_b32 m0, s41
	s_nop 0
	global_load_lds_dwordx4 v[134:135], off
	v_lshl_add_u64 v[134:135], v[134:135], 0, s[44:45]
	s_mov_b32 m0, s42
	s_nop 0
	global_load_lds_dwordx4 v[134:135], off
	s_mov_b32 m0, s43
	v_add_u32_e32 v148, s20, v216
	v_sub_u32_e32 v148, v148, v166
	v_cvt_f32_i32_e32 v148, v148
	v_mul_f32_e32 v148, v164, v148
	v_add_f32_e32 v149, v164, v148
	v_add_f32_e32 v150, v164, v149
	v_add_f32_e32 v151, v164, v150
	v_add_f32_e32 v152, v223, v151
	v_add_f32_e32 v153, v164, v152
	v_add_f32_e32 v154, v164, v153
	v_add_f32_e32 v155, v164, v154
	v_add_f32_e32 v156, v223, v155
	v_add_f32_e32 v157, v164, v156
	v_add_f32_e32 v158, v164, v157
	v_add_f32_e32 v159, v164, v158
	v_add_f32_e32 v160, v223, v159
	v_add_f32_e32 v161, v164, v160
	v_add_f32_e32 v162, v164, v161
	v_add_f32_e32 v163, v164, v162
	v_sub_f32_e64 v148, -|v148|, v221
	v_sub_f32_e64 v149, -|v149|, v221
	v_sub_f32_e64 v150, -|v150|, v221
	v_sub_f32_e64 v151, -|v151|, v221
	v_sub_f32_e64 v152, -|v152|, v221
	v_sub_f32_e64 v153, -|v153|, v221
	v_sub_f32_e64 v154, -|v154|, v221
	v_sub_f32_e64 v155, -|v155|, v221
	v_sub_f32_e64 v156, -|v156|, v221
	v_sub_f32_e64 v157, -|v157|, v221
	v_sub_f32_e64 v158, -|v158|, v221
	v_sub_f32_e64 v159, -|v159|, v221
	v_sub_f32_e64 v160, -|v160|, v221
	v_sub_f32_e64 v161, -|v161|, v221
	v_sub_f32_e64 v162, -|v162|, v221
	v_sub_f32_e64 v163, -|v163|, v221
	v_xor_b32_e32 v249, 0x60, v246
	v_xor_b32_e32 v251, 0xa0, v246
	v_xor_b32_e32 v252, 0xc0, v246
	v_xor_b32_e32 v253, 0xe0, v246
	v_add_u32_e32 v228, s15, v222
	s_waitcnt lgkmcnt(6)
	v_mfma_f32_32x32x16_bf16 v[132:147], v[180:183], v[184:187], v[148:163]
	ds_read_b128 v[180:183], v249
	ds_read_b128 v[184:187], v219 offset:3072
	s_waitcnt lgkmcnt(6)
	v_mfma_f32_32x32x16_bf16 v[148:163], v[188:191], v[192:195], v[148:163]
	ds_read_b128 v[188:191], v251
	ds_read_b128 v[192:195], v219 offset:5120
	s_waitcnt lgkmcnt(6)
	v_mfma_f32_32x32x16_bf16 v[148:163], v[200:203], v[204:207], v[148:163]
	ds_read_b128 v[200:203], v252
	ds_read_b128 v[204:207], v219 offset:6144
	s_waitcnt lgkmcnt(6)
	v_mfma_f32_32x32x16_bf16 v[148:163], v[208:211], v[212:215], v[148:163]
	ds_read_b128 v[208:211], v253
	ds_read_b128 v[212:215], v219 offset:7168
	s_waitcnt lgkmcnt(6)
	v_mfma_f32_32x32x16_bf16 v[148:163], v[180:183], v[184:187], v[148:163]
	ds_read_b64_tr_b16 v[180:181], v228 offset:32768
	ds_read_b64_tr_b16 v[182:183], v228 offset:33280
	ds_read_b64_tr_b16 v[184:185], v228 offset:33792
	ds_read_b64_tr_b16 v[186:187], v228 offset:34304
	s_waitcnt lgkmcnt(8)
	v_mfma_f32_32x32x16_bf16 v[132:147], v[188:191], v[192:195], v[132:147]
	ds_read_b64_tr_b16 v[188:189], v228 offset:36864
	ds_read_b64_tr_b16 v[190:191], v228 offset:37376
	ds_read_b64_tr_b16 v[192:193], v228 offset:37888
	ds_read_b64_tr_b16 v[194:195], v228 offset:38400
	s_waitcnt lgkmcnt(10)
	v_mfma_f32_32x32x16_bf16 v[132:147], v[200:203], v[204:207], v[132:147]
	ds_read_b64_tr_b16 v[200:201], v228 offset:40960
	ds_read_b64_tr_b16 v[202:203], v228 offset:41472
	ds_read_b64_tr_b16 v[204:205], v228 offset:41984
	ds_read_b64_tr_b16 v[206:207], v228 offset:42496
	s_waitcnt lgkmcnt(12)
	v_mfma_f32_32x32x16_bf16 v[132:147], v[208:211], v[212:215], v[132:147]
	ds_read_b64_tr_b16 v[208:209], v228 offset:45056
	ds_read_b64_tr_b16 v[210:211], v228 offset:45568
	v_exp_f32_e32 v148, v148
	v_exp_f32_e32 v149, v149
	v_exp_f32_e32 v150, v150
	v_exp_f32_e32 v151, v151
	v_exp_f32_e32 v152, v152
	v_exp_f32_e32 v153, v153
	v_exp_f32_e32 v154, v154
	v_exp_f32_e32 v155, v155
	v_exp_f32_e32 v156, v156
	v_exp_f32_e32 v157, v157
	v_exp_f32_e32 v158, v158
	v_exp_f32_e32 v159, v159
	v_exp_f32_e32 v160, v160
	v_exp_f32_e32 v161, v161
	v_exp_f32_e32 v162, v162
	v_exp_f32_e32 v163, v163
	v_add_f32_e32 v170, v170, v148
	v_add_f32_e32 v171, v171, v149
	v_cvt_pk_bf16_f32 v230, v148, v149
	v_add_f32_e32 v170, v170, v150
	v_add_f32_e32 v171, v171, v151
	v_cvt_pk_bf16_f32 v231, v150, v151
	v_add_f32_e32 v170, v170, v152
	v_add_f32_e32 v171, v171, v153
	v_cvt_pk_bf16_f32 v232, v152, v153
	v_add_f32_e32 v170, v170, v154
	v_add_f32_e32 v171, v171, v155
	v_cvt_pk_bf16_f32 v233, v154, v155
	v_add_f32_e32 v170, v170, v156
	v_add_f32_e32 v171, v171, v157
	v_cvt_pk_bf16_f32 v234, v156, v157
	v_add_f32_e32 v170, v170, v158
	v_add_f32_e32 v171, v171, v159
	v_cvt_pk_bf16_f32 v235, v158, v159
	v_add_f32_e32 v170, v170, v160
	v_add_f32_e32 v171, v171, v161
	v_cvt_pk_bf16_f32 v236, v160, v161
	v_add_f32_e32 v170, v170, v162
	v_add_f32_e32 v171, v171, v163
	v_cvt_pk_bf16_f32 v237, v162, v163
	s_waitcnt lgkmcnt(12)
	ds_read_b64_tr_b16 v[212:213], v228 offset:46080
	ds_read_b64_tr_b16 v[214:215], v228 offset:46592
	s_setprio 2
	v_mfma_f32_32x32x16_bf16 v[100:115], v[180:183], v[230:233], v[100:115]
	v_exp_f32_e32 v132, v132
	v_exp_f32_e32 v133, v133
	s_waitcnt lgkmcnt(12)
	v_mfma_f32_32x32x16_bf16 v[100:115], v[184:187], v[234:237], v[100:115]
	v_exp_f32_e32 v134, v134
	v_exp_f32_e32 v135, v135
	v_add_f32_e32 v178, v178, v132
	v_add_f32_e32 v179, v179, v133
	v_cvt_pk_bf16_f32 v238, v132, v133
	s_waitcnt lgkmcnt(10)
	v_mfma_f32_32x32x16_bf16 v[68:83], v[188:191], v[230:233], v[68:83]
	v_exp_f32_e32 v136, v136
	v_exp_f32_e32 v137, v137
	v_add_f32_e32 v178, v178, v134
	v_add_f32_e32 v179, v179, v135
	v_cvt_pk_bf16_f32 v239, v134, v135
	s_waitcnt lgkmcnt(8)
	v_mfma_f32_32x32x16_bf16 v[68:83], v[192:195], v[234:237], v[68:83]
	v_exp_f32_e32 v138, v138
	v_exp_f32_e32 v139, v139
	v_add_f32_e32 v178, v178, v136
	v_add_f32_e32 v179, v179, v137
	v_cvt_pk_bf16_f32 v240, v136, v137
	s_waitcnt lgkmcnt(6)
	v_mfma_f32_32x32x16_bf16 v[34:49], v[200:203], v[230:233], v[34:49]
	v_exp_f32_e32 v140, v140
	v_exp_f32_e32 v141, v141
	v_add_f32_e32 v178, v178, v138
	v_add_f32_e32 v179, v179, v139
	v_cvt_pk_bf16_f32 v241, v138, v139
	s_waitcnt lgkmcnt(4)
	v_mfma_f32_32x32x16_bf16 v[34:49], v[204:207], v[234:237], v[34:49]
	v_exp_f32_e32 v142, v142
	v_exp_f32_e32 v143, v143
	v_add_f32_e32 v178, v178, v140
	v_add_f32_e32 v179, v179, v141
	v_cvt_pk_bf16_f32 v242, v140, v141
	s_waitcnt lgkmcnt(2)
	v_mfma_f32_32x32x16_bf16 v[18:33], v[208:211], v[230:233], v[18:33]
	v_exp_f32_e32 v144, v144
	v_exp_f32_e32 v145, v145
	v_add_f32_e32 v178, v178, v142
	v_add_f32_e32 v179, v179, v143
	v_cvt_pk_bf16_f32 v243, v142, v143
	s_waitcnt lgkmcnt(0)
	v_mfma_f32_32x32x16_bf16 v[18:33], v[212:215], v[234:237], v[18:33]
	v_exp_f32_e32 v146, v146
	v_exp_f32_e32 v147, v147
	v_add_f32_e32 v178, v178, v144
	v_add_f32_e32 v179, v179, v145
	v_cvt_pk_bf16_f32 v244, v144, v145
	s_nop 0
	v_add_f32_e32 v178, v178, v146
	v_add_f32_e32 v179, v179, v147
	v_cvt_pk_bf16_f32 v245, v146, v147
	s_nop 0
	v_mfma_f32_32x32x16_bf16 v[116:131], v[180:183], v[238:241], v[116:131]
	v_mfma_f32_32x32x16_bf16 v[116:131], v[184:187], v[242:245], v[116:131]
	ds_read_b128 v[180:183], v250 offset:8192
	ds_read_b128 v[184:187], v219 offset:4096
	v_mfma_f32_32x32x16_bf16 v[84:99], v[188:191], v[238:241], v[84:99]
	v_mfma_f32_32x32x16_bf16 v[84:99], v[192:195], v[242:245], v[84:99]
	ds_read_b128 v[188:191], v246 offset:8192
	ds_read_b128 v[192:195], v219
	v_mfma_f32_32x32x16_bf16 v[50:65], v[200:203], v[238:241], v[50:65]
	v_mfma_f32_32x32x16_bf16 v[50:65], v[204:207], v[242:245], v[50:65]
	ds_read_b128 v[200:203], v247 offset:8192
	ds_read_b128 v[204:207], v219 offset:1024
	v_mfma_f32_32x32x16_bf16 v[2:17], v[208:211], v[238:241], v[2:17]
	v_mfma_f32_32x32x16_bf16 v[2:17], v[212:215], v[242:245], v[2:17]
	ds_read_b128 v[208:211], v248 offset:8192
	ds_read_b128 v[212:215], v219 offset:2048
	s_setprio 0
	v_add3_u32 v148, s20, v216, 32
	v_sub_u32_e32 v148, v148, v166
	v_cvt_f32_i32_e32 v148, v148
	v_mul_f32_e32 v148, v164, v148
	v_add_f32_e32 v149, v164, v148
	v_add_f32_e32 v150, v164, v149
	v_add_f32_e32 v151, v164, v150
	v_add_f32_e32 v152, v223, v151
	v_add_f32_e32 v153, v164, v152
	v_add_f32_e32 v154, v164, v153
	v_add_f32_e32 v155, v164, v154
	v_add_f32_e32 v156, v223, v155
	v_add_f32_e32 v157, v164, v156
	v_add_f32_e32 v158, v164, v157
	v_add_f32_e32 v159, v164, v158
	v_add_f32_e32 v160, v223, v159
	v_add_f32_e32 v161, v164, v160
	v_add_f32_e32 v162, v164, v161
	v_add_f32_e32 v163, v164, v162
	v_sub_f32_e64 v148, -|v148|, v221
	v_sub_f32_e64 v149, -|v149|, v221
	v_sub_f32_e64 v150, -|v150|, v221
	v_sub_f32_e64 v151, -|v151|, v221
	v_sub_f32_e64 v152, -|v152|, v221
	v_sub_f32_e64 v153, -|v153|, v221
	v_sub_f32_e64 v154, -|v154|, v221
	v_sub_f32_e64 v155, -|v155|, v221
	v_sub_f32_e64 v156, -|v156|, v221
	v_sub_f32_e64 v157, -|v157|, v221
	v_sub_f32_e64 v158, -|v158|, v221
	v_sub_f32_e64 v159, -|v159|, v221
	v_sub_f32_e64 v160, -|v160|, v221
	v_sub_f32_e64 v161, -|v161|, v221
	v_sub_f32_e64 v162, -|v162|, v221
	v_sub_f32_e64 v163, -|v163|, v221
	s_nop 1
	s_waitcnt lgkmcnt(6)
	v_mfma_f32_32x32x16_bf16 v[132:147], v[180:183], v[184:187], v[148:163]
	ds_read_b128 v[180:183], v249 offset:8192
	ds_read_b128 v[184:187], v219 offset:3072
	s_waitcnt lgkmcnt(6)
	v_mfma_f32_32x32x16_bf16 v[148:163], v[188:191], v[192:195], v[148:163]
	ds_read_b128 v[188:191], v251 offset:8192
	ds_read_b128 v[192:195], v219 offset:5120
	s_waitcnt lgkmcnt(6)
	v_mfma_f32_32x32x16_bf16 v[148:163], v[200:203], v[204:207], v[148:163]
	ds_read_b128 v[200:203], v252 offset:8192
	ds_read_b128 v[204:207], v219 offset:6144
	s_waitcnt lgkmcnt(6)
	v_mfma_f32_32x32x16_bf16 v[148:163], v[208:211], v[212:215], v[148:163]
	ds_read_b128 v[208:211], v253 offset:8192
	ds_read_b128 v[212:215], v219 offset:7168
	s_waitcnt lgkmcnt(6)
	v_mfma_f32_32x32x16_bf16 v[148:163], v[180:183], v[184:187], v[148:163]
	ds_read_b64_tr_b16 v[180:181], v228 offset:34816
	ds_read_b64_tr_b16 v[182:183], v228 offset:35328
	ds_read_b64_tr_b16 v[184:185], v228 offset:35840
	ds_read_b64_tr_b16 v[186:187], v228 offset:36352
	s_waitcnt lgkmcnt(8)
	v_mfma_f32_32x32x16_bf16 v[132:147], v[188:191], v[192:195], v[132:147]
	ds_read_b64_tr_b16 v[188:189], v228 offset:38912
	ds_read_b64_tr_b16 v[190:191], v228 offset:39424
	ds_read_b64_tr_b16 v[192:193], v228 offset:39936
	ds_read_b64_tr_b16 v[194:195], v228 offset:40448
	s_waitcnt lgkmcnt(10)
	v_mfma_f32_32x32x16_bf16 v[132:147], v[200:203], v[204:207], v[132:147]
	ds_read_b64_tr_b16 v[200:201], v228 offset:43008
	ds_read_b64_tr_b16 v[202:203], v228 offset:43520
	ds_read_b64_tr_b16 v[204:205], v228 offset:44032
	ds_read_b64_tr_b16 v[206:207], v228 offset:44544
	s_waitcnt lgkmcnt(12)
	v_mfma_f32_32x32x16_bf16 v[132:147], v[208:211], v[212:215], v[132:147]
	ds_read_b64_tr_b16 v[208:209], v228 offset:47104
	ds_read_b64_tr_b16 v[210:211], v228 offset:47616
	v_exp_f32_e32 v148, v148
	v_exp_f32_e32 v149, v149
	v_exp_f32_e32 v150, v150
	v_exp_f32_e32 v151, v151
	v_exp_f32_e32 v152, v152
	v_exp_f32_e32 v153, v153
	v_exp_f32_e32 v154, v154
	v_exp_f32_e32 v155, v155
	v_exp_f32_e32 v156, v156
	v_exp_f32_e32 v157, v157
	v_exp_f32_e32 v158, v158
	v_exp_f32_e32 v159, v159
	v_exp_f32_e32 v160, v160
	v_exp_f32_e32 v161, v161
	v_exp_f32_e32 v162, v162
	v_exp_f32_e32 v163, v163
	v_add_f32_e32 v170, v170, v148
	v_add_f32_e32 v171, v171, v149
	v_cvt_pk_bf16_f32 v230, v148, v149
	v_add_f32_e32 v170, v170, v150
	v_add_f32_e32 v171, v171, v151
	v_cvt_pk_bf16_f32 v231, v150, v151
	v_add_f32_e32 v170, v170, v152
	v_add_f32_e32 v171, v171, v153
	v_cvt_pk_bf16_f32 v232, v152, v153
	v_add_f32_e32 v170, v170, v154
	v_add_f32_e32 v171, v171, v155
	v_cvt_pk_bf16_f32 v233, v154, v155
	v_add_f32_e32 v170, v170, v156
	v_add_f32_e32 v171, v171, v157
	v_cvt_pk_bf16_f32 v234, v156, v157
	v_add_f32_e32 v170, v170, v158
	v_add_f32_e32 v171, v171, v159
	v_cvt_pk_bf16_f32 v235, v158, v159
	v_add_f32_e32 v170, v170, v160
	v_add_f32_e32 v171, v171, v161
	v_cvt_pk_bf16_f32 v236, v160, v161
	v_add_f32_e32 v170, v170, v162
	v_add_f32_e32 v171, v171, v163
	v_cvt_pk_bf16_f32 v237, v162, v163
	s_waitcnt lgkmcnt(12)
	ds_read_b64_tr_b16 v[212:213], v228 offset:48128
	ds_read_b64_tr_b16 v[214:215], v228 offset:48640
	s_cmp_le_i32 s12, 1
	s_cbranch_scc1 .Latt_first_b
	s_setprio 2
	v_mfma_f32_32x32x16_bf16 v[100:115], v[180:183], v[230:233], v[100:115]
	v_exp_f32_e32 v132, v132
	v_exp_f32_e32 v133, v133
	s_waitcnt lgkmcnt(12)
	v_mfma_f32_32x32x16_bf16 v[100:115], v[184:187], v[234:237], v[100:115]
	v_exp_f32_e32 v134, v134
	v_exp_f32_e32 v135, v135
	v_add_f32_e32 v178, v178, v132
	v_add_f32_e32 v179, v179, v133
	v_cvt_pk_bf16_f32 v238, v132, v133
	s_waitcnt lgkmcnt(10)
	v_mfma_f32_32x32x16_bf16 v[68:83], v[188:191], v[230:233], v[68:83]
	v_exp_f32_e32 v136, v136
	v_exp_f32_e32 v137, v137
	v_add_f32_e32 v178, v178, v134
	v_add_f32_e32 v179, v179, v135
	v_cvt_pk_bf16_f32 v239, v134, v135
	s_waitcnt lgkmcnt(8)
	v_mfma_f32_32x32x16_bf16 v[68:83], v[192:195], v[234:237], v[68:83]
	v_exp_f32_e32 v138, v138
	v_exp_f32_e32 v139, v139
	v_add_f32_e32 v178, v178, v136
	v_add_f32_e32 v179, v179, v137
	v_cvt_pk_bf16_f32 v240, v136, v137
	s_waitcnt lgkmcnt(6)
	v_mfma_f32_32x32x16_bf16 v[34:49], v[200:203], v[230:233], v[34:49]
	v_exp_f32_e32 v140, v140
	v_exp_f32_e32 v141, v141
	v_add_f32_e32 v178, v178, v138
	v_add_f32_e32 v179, v179, v139
	v_cvt_pk_bf16_f32 v241, v138, v139
	s_waitcnt lgkmcnt(4)
	v_mfma_f32_32x32x16_bf16 v[34:49], v[204:207], v[234:237], v[34:49]
	v_exp_f32_e32 v142, v142
	v_exp_f32_e32 v143, v143
	v_add_f32_e32 v178, v178, v140
	v_add_f32_e32 v179, v179, v141
	v_cvt_pk_bf16_f32 v242, v140, v141
	s_waitcnt lgkmcnt(2)
	v_mfma_f32_32x32x16_bf16 v[18:33], v[208:211], v[230:233], v[18:33]
	v_exp_f32_e32 v144, v144
	v_exp_f32_e32 v145, v145
	v_add_f32_e32 v178, v178, v142
	v_add_f32_e32 v179, v179, v143
	v_cvt_pk_bf16_f32 v243, v142, v143
	s_waitcnt lgkmcnt(0)
	v_mfma_f32_32x32x16_bf16 v[18:33], v[212:215], v[234:237], v[18:33]
	v_exp_f32_e32 v146, v146
	v_exp_f32_e32 v147, v147
	v_add_f32_e32 v178, v178, v144
	v_add_f32_e32 v179, v179, v145
	v_cvt_pk_bf16_f32 v244, v144, v145
	s_nop 0
	v_add_f32_e32 v178, v178, v146
	v_add_f32_e32 v179, v179, v147
	v_cvt_pk_bf16_f32 v245, v146, v147
	s_nop 0
	s_cmp_ge_i32 s13, s77
	s_cbranch_scc1 .Latt_fa_flush
	s_cmp_eq_u32 s13, s78
	s_cbranch_scc1 .Latt_fa_flush
	s_mov_b32 s101, 1
	s_branch .LBB0_981
